# all four big GEMMs (w_in, w_out, ffn1, ffn2) rewritten by hand: LDS-DMA ring + pipelined fragments, batched-load residual epilogue
# speedup vs baseline: 1.1313x; 1.0998x over previous
.LBB0_34:
	s_andn2_b64 vcc, exec, s[36:37]
	v_writelane_b32 v235, s61, 55
	s_cbranch_vccnz .LBB0_764
	s_add_i32 s30, s64, -1
	s_mul_hi_i32 s31, s30, 0x66666667
	s_lshr_b32 s35, s31, 31
	s_ashr_i32 s31, s31, 2
	s_add_i32 s36, s31, s35
	s_mul_i32 s31, s36, 10
	s_sub_i32 s5, s30, s31
	s_lshl_b32 s30, s64, 5
	s_ashr_i32 s31, s30, 31
	s_lshl_b64 s[30:31], s[30:31], 2
	v_readlane_b32 s4, v237, 59
	s_add_u32 s6, s4, s30
	v_readlane_b32 s4, v237, 60
	s_addc_u32 s7, s4, s31
	s_add_i32 s30, s64, 8
	v_writelane_b32 v235, s6, 56
	s_cmp_lt_u32 s30, 19
	s_cselect_b32 s17, s69, s95
	v_writelane_b32 v235, s7, 57
	s_cselect_b32 s16, s68, s94
	s_cselect_b32 s31, s71, s67
	s_cselect_b32 s30, s70, s66
	s_lshl_b32 s6, s36, 10
	s_ashr_i32 s7, s6, 31
	v_writelane_b32 v235, s6, 58
	s_mul_i32 s4, s36, 3
	s_ashr_i32 s37, s36, 31
	v_writelane_b32 v235, s7, 59
	s_lshl_b32 s6, s36, 8
	v_writelane_b32 v235, s4, 60
	s_ashr_i32 s7, s6, 31
	v_writelane_b32 v235, s6, 61
	s_cmp_eq_u32 s5, 8
	s_cbranch_scc1 .Lgm_f1_entry
	s_cmp_eq_u32 s5, 9
	s_cbranch_scc1 .Lgm_f2_entry
	s_cmp_eq_u32 s5, 6
	s_cbranch_scc1 .Lgm_wo_entry
	s_cmp_eq_u32 s5, 1
	s_cbranch_scc1 .Lgm_wi_entry
	s_cmp_lt_i32 s5, 4
	s_mov_b64 s[38:39], -1
	v_writelane_b32 v235, s7, 62
	v_writelane_b32 v235, s5, 63
	s_cbranch_scc1 .LBB0_561
	s_mul_i32 s38, s36, 0x12000
	v_readlane_b32 s4, v236, 3
	s_mul_hi_i32 s35, s36, 0x12000
	v_readlane_b32 s5, v236, 4
	s_add_u32 s54, s4, s38
	s_addc_u32 s55, s5, s35
	s_add_i32 s56, s61, 0xff
	v_readlane_b32 s4, v235, 63
	s_cmp_lt_i32 s4, 7
	s_mov_b64 s[38:39], -1
	s_cbranch_scc1 .LBB0_192
	v_readlane_b32 s4, v235, 63
	s_cmp_lt_i32 s4, 8
	s_cbranch_scc1 .LBB0_182
	s_lshl_b64 s[44:45], s[36:37], 23
	v_readlane_b32 s4, v235, 63
	s_cmp_lt_i32 s4, 9
	s_cbranch_scc1 .LBB0_158
	v_readlane_b32 s4, v235, 63
	s_cmp_eq_u32 s4, 9
	s_cbranch_scc0 .LBB0_157
	s_branch .LBB0_157

.Lgm_f2_entry:
	s_add_u32 s56, s96, 0x9484000
	s_addc_u32 s57, s97, 0
	s_add_u32 s58, s96, 0x7c84000
	s_addc_u32 s59, s97, 0
	s_mov_b32 s98, s58
	s_mov_b32 s99, s59
	s_mul_i32 s4, s36, 0x12000
	s_add_u32 s100, s96, 0x2e05000
	s_addc_u32 s101, s97, 0
	s_add_u32 s100, s100, s4
	s_addc_u32 s101, s101, 0
	s_mov_b32 s52, s61
	s_mov_b32 s53, s63
	s_movk_i32 s54, 0x100
	s_cmp_ge_u32 s53, s54
	s_cbranch_scc1 .Lgm_f2_exit
	s_mov_b32 s30, 0
	s_mov_b32 s4, s53
.Lgm_f2_cnt:
	s_add_u32 s30, s30, 64
	s_add_u32 s4, s4, s52
	s_cmp_lt_u32 s4, s54
	s_cbranch_scc1 .Lgm_f2_cnt
	s_add_u32 s48, s96, 0x3a24000
	s_addc_u32 s49, s97, 0
	s_mul_i32 s4, s36, 0x800000
	s_add_u32 s50, s96, 0x1d80000
	s_addc_u32 s51, s97, 0
	s_add_u32 s50, s50, s4
	s_addc_u32 s51, s51, 0
	v_and_b32_e32 v0, 63, v206
	v_lshrrev_b32_e32 v1, 6, v206
	v_lshrrev_b32_e32 v3, 3, v0
	v_and_b32_e32 v4, 7, v0
	v_readfirstlane_b32 s42, v1
	v_xor_b32_e32 v4, v4, v3
	v_lshl_add_u32 v3, v1, 3, v3
	v_lshlrev_b32_e32 v3, 13, v3
	v_lshl_add_u32 v148, v4, 4, v3
	v_add_u32_e32 v149, 0x80000, v148
	v_add_u32_e32 v150, 0x100000, v148
	v_and_b32_e32 v5, 15, v0
	v_lshrrev_b32_e32 v6, 4, v0
	v_and_b32_e32 v7, 7, v5
	v_xor_b32_e32 v7, v7, v6
	v_lshlrev_b32_e32 v7, 4, v7
	v_lshrrev_b32_e32 v8, 1, v1
	v_and_b32_e32 v9, 1, v1
	v_mul_u32_u24_e32 v10, 48, v8
	v_add_u32_e32 v11, v10, v5
	v_lshl_add_u32 v151, v11, 7, v7
	v_xor_b32_e32 v152, 64, v151
	v_lshl_add_u32 v11, v9, 6, v5
	v_lshl_add_u32 v153, v11, 7, v7
	v_add_u32_e32 v153, 0x6000, v153
	v_xor_b32_e32 v154, 64, v153
	s_mul_i32 s5, s42, 4352
	s_mov_b32 s6, 0x1ec10
	s_cmp_lt_u32 s42, 4
	s_cselect_b32 s6, 0x1e000, s6
	s_add_u32 s5, s5, s6
	v_mul_u32_u24_e32 v11, 1088, v6
	v_lshl_add_u32 v11, v5, 2, v11
	v_add_u32_e32 v155, s5, v11
	v_mul_u32_u24_e32 v11, 272, v6
	v_lshl_add_u32 v11, v5, 4, v11
	v_add_u32_e32 v156, s5, v11
	v_add_u32_e32 v11, v10, v6
	v_lshlrev_b32_e32 v12, 6, v9
	v_lshl_add_u32 v12, v5, 2, v12
	s_mov_b32 s4, 0x1000
	v_mul_lo_u32 v13, v11, s4
	v_lshl_add_u32 v157, v12, 2, v13
	v_mov_b32_e32 v159, v11
	v_lshlrev_b32_e32 v160, 2, v12
	s_lshl_b32 s42, s42, 10
	v_mov_b32_e32 v44, 0
	v_mov_b32_e32 v45, 0
	v_mov_b32_e32 v46, 0
	v_mov_b32_e32 v47, 0
	v_mov_b32_e32 v48, 0
	v_mov_b32_e32 v49, 0
	v_mov_b32_e32 v50, 0
	v_mov_b32_e32 v51, 0
	v_mov_b32_e32 v52, 0
	v_mov_b32_e32 v53, 0
	v_mov_b32_e32 v54, 0
	v_mov_b32_e32 v55, 0
	v_mov_b32_e32 v56, 0
	v_mov_b32_e32 v57, 0
	v_mov_b32_e32 v58, 0
	v_mov_b32_e32 v59, 0
	v_mov_b32_e32 v60, 0
	v_mov_b32_e32 v61, 0
	v_mov_b32_e32 v62, 0
	v_mov_b32_e32 v63, 0
	v_mov_b32_e32 v64, 0
	v_mov_b32_e32 v65, 0
	v_mov_b32_e32 v66, 0
	v_mov_b32_e32 v67, 0
	v_mov_b32_e32 v68, 0
	v_mov_b32_e32 v69, 0
	v_mov_b32_e32 v70, 0
	v_mov_b32_e32 v71, 0
	v_mov_b32_e32 v72, 0
	v_mov_b32_e32 v73, 0
	v_mov_b32_e32 v74, 0
	v_mov_b32_e32 v75, 0
	v_mov_b32_e32 v76, 0
	v_mov_b32_e32 v77, 0
	v_mov_b32_e32 v78, 0
	v_mov_b32_e32 v79, 0
	v_mov_b32_e32 v80, 0
	v_mov_b32_e32 v81, 0
	v_mov_b32_e32 v82, 0
	v_mov_b32_e32 v83, 0
	v_mov_b32_e32 v84, 0
	v_mov_b32_e32 v85, 0
	v_mov_b32_e32 v86, 0
	v_mov_b32_e32 v87, 0
	v_mov_b32_e32 v88, 0
	v_mov_b32_e32 v89, 0
	v_mov_b32_e32 v90, 0
	v_mov_b32_e32 v91, 0
	s_mov_b32 s31, 0
	s_mov_b32 s34, 0
	s_mov_b32 s35, s53
	s_mov_b32 s38, s53
	s_mov_b32 s39, 0
	s_mov_b32 s40, 0
	s_mov_b32 s41, s42
	s_and_b32 s4, s38, 31
	s_mul_i32 s4, s4, 0x180000
	s_add_u32 s44, s48, s4
	s_addc_u32 s45, s49, 0
	s_lshr_b32 s4, s38, 5
	s_mul_i32 s4, s4, 0x100000
	s_add_u32 s46, s50, s4
	s_addc_u32 s47, s51, 0
	s_add_u32 m0, s41, 0x0
	s_nop 0
	global_load_lds_dwordx4 v148, s[44:45]
	s_add_u32 m0, s41, 0x2000
	s_nop 0
	global_load_lds_dwordx4 v149, s[44:45]
	s_add_u32 m0, s41, 0x4000
	s_nop 0
	global_load_lds_dwordx4 v150, s[44:45]
	s_add_u32 m0, s41, 0x6000
	s_nop 0
	global_load_lds_dwordx4 v148, s[46:47]
	s_add_u32 m0, s41, 0x8000
	s_nop 0
	global_load_lds_dwordx4 v149, s[46:47]
	s_add_u32 s39, s39, 1
	s_add_u32 s44, s44, 0x80
	s_addc_u32 s45, s45, 0
	s_add_u32 s46, s46, 0x80
	s_addc_u32 s47, s47, 0
	s_cmp_lt_u32 s39, 64
	s_cbranch_scc1 .Lgm_f2_dadv1
	s_mov_b32 s39, 0
	s_add_u32 s4, s38, s52
	s_cmp_lt_u32 s4, s54
	s_cselect_b32 s38, s4, s38
	s_and_b32 s4, s38, 31
	s_mul_i32 s4, s4, 0x180000
	s_add_u32 s44, s48, s4
	s_addc_u32 s45, s49, 0
	s_lshr_b32 s4, s38, 5
	s_mul_i32 s4, s4, 0x100000
	s_add_u32 s46, s50, s4
	s_addc_u32 s47, s51, 0
.Lgm_f2_dadv1:
	s_add_u32 s41, s41, 0xa000
	s_sub_u32 s4, s41, 0x1e000
	s_cmp_ge_u32 s41, 0x1e000
	s_cselect_b32 s41, s4, s41
	s_add_u32 m0, s41, 0x0
	s_nop 0
	global_load_lds_dwordx4 v148, s[44:45]
	s_add_u32 m0, s41, 0x2000
	s_nop 0
	global_load_lds_dwordx4 v149, s[44:45]
	s_add_u32 m0, s41, 0x4000
	s_nop 0
	global_load_lds_dwordx4 v150, s[44:45]
	s_add_u32 m0, s41, 0x6000
	s_nop 0
	global_load_lds_dwordx4 v148, s[46:47]
	s_add_u32 m0, s41, 0x8000
	s_nop 0
	global_load_lds_dwordx4 v149, s[46:47]
	s_add_u32 s39, s39, 1
	s_add_u32 s44, s44, 0x80
	s_addc_u32 s45, s45, 0
	s_add_u32 s46, s46, 0x80
	s_addc_u32 s47, s47, 0
	s_cmp_lt_u32 s39, 64
	s_cbranch_scc1 .Lgm_f2_dadv2
	s_mov_b32 s39, 0
	s_add_u32 s4, s38, s52
	s_cmp_lt_u32 s4, s54
	s_cselect_b32 s38, s4, s38
	s_and_b32 s4, s38, 31
	s_mul_i32 s4, s4, 0x180000
	s_add_u32 s44, s48, s4
	s_addc_u32 s45, s49, 0
	s_lshr_b32 s4, s38, 5
	s_mul_i32 s4, s4, 0x100000
	s_add_u32 s46, s50, s4
	s_addc_u32 s47, s51, 0

.Lgm_f2_join:
	s_add_u32 s39, s39, 1
	s_add_u32 s44, s44, 0x80
	s_addc_u32 s45, s45, 0
	s_add_u32 s46, s46, 0x80
	s_addc_u32 s47, s47, 0
	s_cmp_lt_u32 s39, 64
	s_cbranch_scc1 .Lgm_f2_dadv3
	s_mov_b32 s39, 0
	s_add_u32 s4, s38, s52
	s_cmp_lt_u32 s4, s54
	s_cselect_b32 s38, s4, s38
	s_and_b32 s4, s38, 31
	s_mul_i32 s4, s4, 0x180000
	s_add_u32 s44, s48, s4
	s_addc_u32 s45, s49, 0
	s_lshr_b32 s4, s38, 5
	s_mul_i32 s4, s4, 0x100000
	s_add_u32 s46, s50, s4
	s_addc_u32 s47, s51, 0
.Lgm_f2_dadv3:
	ds_read_b128 v[120:123], v152 offset:0
	ds_read_b128 v[124:127], v152 offset:2048
	ds_read_b128 v[128:131], v152 offset:4096
	ds_read_b128 v[132:135], v154 offset:0
	ds_read_b128 v[136:139], v154 offset:2048
	ds_read_b128 v[140:143], v154 offset:4096
	ds_read_b128 v[144:147], v154 offset:6144
	s_waitcnt lgkmcnt(10)
	v_mfma_f32_16x16x32_bf16 v[44:47], v[92:95], v[104:107], v[44:47]
	v_mfma_f32_16x16x32_bf16 v[60:63], v[96:99], v[104:107], v[60:63]
	v_mfma_f32_16x16x32_bf16 v[76:79], v[100:103], v[104:107], v[76:79]
	s_waitcnt lgkmcnt(9)
	v_mfma_f32_16x16x32_bf16 v[48:51], v[92:95], v[108:111], v[48:51]
	v_mfma_f32_16x16x32_bf16 v[64:67], v[96:99], v[108:111], v[64:67]
	v_mfma_f32_16x16x32_bf16 v[80:83], v[100:103], v[108:111], v[80:83]
	s_waitcnt lgkmcnt(8)
	v_mfma_f32_16x16x32_bf16 v[52:55], v[92:95], v[112:115], v[52:55]
	v_mfma_f32_16x16x32_bf16 v[68:71], v[96:99], v[112:115], v[68:71]
	v_mfma_f32_16x16x32_bf16 v[84:87], v[100:103], v[112:115], v[84:87]
	s_waitcnt lgkmcnt(7)
	v_mfma_f32_16x16x32_bf16 v[56:59], v[92:95], v[116:119], v[56:59]
	v_mfma_f32_16x16x32_bf16 v[72:75], v[96:99], v[116:119], v[72:75]
	v_mfma_f32_16x16x32_bf16 v[88:91], v[100:103], v[116:119], v[88:91]
	s_waitcnt lgkmcnt(0)
	s_add_u32 s34, s34, 1
	s_cmp_lt_u32 s34, 64
	s_cbranch_scc1 .Lgm_f2_next
	v_mfma_f32_16x16x32_bf16 v[44:47], v[120:123], v[132:135], v[44:47]
	v_mfma_f32_16x16x32_bf16 v[60:63], v[124:127], v[132:135], v[60:63]
	v_mfma_f32_16x16x32_bf16 v[76:79], v[128:131], v[132:135], v[76:79]
	v_mfma_f32_16x16x32_bf16 v[48:51], v[120:123], v[136:139], v[48:51]
	v_mfma_f32_16x16x32_bf16 v[64:67], v[124:127], v[136:139], v[64:67]
	v_mfma_f32_16x16x32_bf16 v[80:83], v[128:131], v[136:139], v[80:83]
	v_mfma_f32_16x16x32_bf16 v[52:55], v[120:123], v[140:143], v[52:55]
	v_mfma_f32_16x16x32_bf16 v[68:71], v[124:127], v[140:143], v[68:71]
	v_mfma_f32_16x16x32_bf16 v[84:87], v[128:131], v[140:143], v[84:87]
	v_mfma_f32_16x16x32_bf16 v[56:59], v[120:123], v[144:147], v[56:59]
	v_mfma_f32_16x16x32_bf16 v[72:75], v[124:127], v[144:147], v[72:75]
	v_mfma_f32_16x16x32_bf16 v[88:91], v[128:131], v[144:147], v[88:91]
	s_and_b32 s6, s35, 31
	s_mul_i32 s6, s6, 192
	s_lshr_b32 s7, s35, 5
	s_lshl_b32 s7, s7, 7
	s_nop 7
	s_mul_i32 s4, s6, 0x1000
	s_lshl_b32 s5, s7, 2
	s_add_u32 s4, s4, s5
	v_add_u32_e32 v158, s4, v157
	v_add_u32_e32 v161, s6, v159
	v_lshl_add_u32 v162, s7, 2, v160
	s_sub_i32 s4, s6, 0xc00
	s_max_i32 s4, s4, 0
	s_lshr_b32 s4, s4, 10
	s_add_i32 s5, s6, -2881
	s_max_i32 s5, s5, 0
	s_lshr_b32 s5, s5, 10
	s_movk_i32 s7, 0x1400
	s_cmp_eq_u32 s4, 0
	s_cselect_b32 s7, 0x1000, s7
	s_mul_i32 s4, s4, 0x6000
	s_mul_i32 s5, s5, 0x6000
	v_mov_b32_e32 v163, v158
	v_add_u32_e32 v164, 0, v161
	v_cmp_gt_u32_e32 vcc, 0x1000, v164
	v_mov_b32_e32 v0, s98
	v_mov_b32_e32 v1, s99
	v_mov_b32_e32 v3, s58
	v_cndmask_b32_e32 v0, v0, v3, vcc
	v_mov_b32_e32 v3, s59
	v_cndmask_b32_e32 v1, v1, v3, vcc
	v_add_co_u32_e32 v0, vcc, v0, v163
	s_nop 1
	v_addc_co_u32_e32 v1, vcc, 0, v1, vcc
	global_load_dwordx4 v[92:95], v[0:1], off
	v_add_u32_e32 v163, 0x4000, v163
	v_add_u32_e32 v164, 4, v161
	v_cmp_gt_u32_e32 vcc, 0x1000, v164
	v_mov_b32_e32 v0, s98
	v_mov_b32_e32 v1, s99
	v_mov_b32_e32 v3, s58
	v_cndmask_b32_e32 v0, v0, v3, vcc
	v_mov_b32_e32 v3, s59
	v_cndmask_b32_e32 v1, v1, v3, vcc
	v_add_co_u32_e32 v0, vcc, v0, v163
	s_nop 1
	v_addc_co_u32_e32 v1, vcc, 0, v1, vcc
	global_load_dwordx4 v[96:99], v[0:1], off
	v_add_u32_e32 v163, 0x4000, v163
	v_add_u32_e32 v164, 8, v161
	v_cmp_gt_u32_e32 vcc, 0x1000, v164
	v_mov_b32_e32 v0, s98
	v_mov_b32_e32 v1, s99
	v_mov_b32_e32 v3, s58
	v_cndmask_b32_e32 v0, v0, v3, vcc
	v_mov_b32_e32 v3, s59
	v_cndmask_b32_e32 v1, v1, v3, vcc
	v_add_co_u32_e32 v0, vcc, v0, v163
	s_nop 1
	v_addc_co_u32_e32 v1, vcc, 0, v1, vcc
	global_load_dwordx4 v[100:103], v[0:1], off
	v_add_u32_e32 v163, 0x4000, v163
	v_add_u32_e32 v164, 12, v161
	v_cmp_gt_u32_e32 vcc, 0x1000, v164
	v_mov_b32_e32 v0, s98
	v_mov_b32_e32 v1, s99
	v_mov_b32_e32 v3, s58
	v_cndmask_b32_e32 v0, v0, v3, vcc
	v_mov_b32_e32 v3, s59
	v_cndmask_b32_e32 v1, v1, v3, vcc
	v_add_co_u32_e32 v0, vcc, v0, v163
	s_nop 1
	v_addc_co_u32_e32 v1, vcc, 0, v1, vcc
	global_load_dwordx4 v[104:107], v[0:1], off
	v_add_u32_e32 v163, 0x4000, v163
	v_add_u32_e32 v164, 16, v161
	v_cmp_gt_u32_e32 vcc, 0x1000, v164
	v_mov_b32_e32 v0, s98
	v_mov_b32_e32 v1, s99
	v_mov_b32_e32 v3, s58
	v_cndmask_b32_e32 v0, v0, v3, vcc
	v_mov_b32_e32 v3, s59
	v_cndmask_b32_e32 v1, v1, v3, vcc
	v_add_co_u32_e32 v0, vcc, v0, v163
	s_nop 1
	v_addc_co_u32_e32 v1, vcc, 0, v1, vcc
	global_load_dwordx4 v[108:111], v[0:1], off
	v_add_u32_e32 v163, 0x4000, v163
	v_add_u32_e32 v164, 20, v161
	v_cmp_gt_u32_e32 vcc, 0x1000, v164
	v_mov_b32_e32 v0, s98
	v_mov_b32_e32 v1, s99
	v_mov_b32_e32 v3, s58
	v_cndmask_b32_e32 v0, v0, v3, vcc
	v_mov_b32_e32 v3, s59
	v_cndmask_b32_e32 v1, v1, v3, vcc
	v_add_co_u32_e32 v0, vcc, v0, v163
	s_nop 1
	v_addc_co_u32_e32 v1, vcc, 0, v1, vcc
	global_load_dwordx4 v[112:115], v[0:1], off
	v_add_u32_e32 v163, 0x4000, v163
	v_add_u32_e32 v164, 24, v161
	v_cmp_gt_u32_e32 vcc, 0x1000, v164
	v_mov_b32_e32 v0, s98
	v_mov_b32_e32 v1, s99
	v_mov_b32_e32 v3, s58
	v_cndmask_b32_e32 v0, v0, v3, vcc
	v_mov_b32_e32 v3, s59
	v_cndmask_b32_e32 v1, v1, v3, vcc
	v_add_co_u32_e32 v0, vcc, v0, v163
	s_nop 1
	v_addc_co_u32_e32 v1, vcc, 0, v1, vcc
	global_load_dwordx4 v[116:119], v[0:1], off
	v_add_u32_e32 v163, 0x4000, v163
	v_add_u32_e32 v164, 28, v161
	v_cmp_gt_u32_e32 vcc, 0x1000, v164
	v_mov_b32_e32 v0, s98
	v_mov_b32_e32 v1, s99
	v_mov_b32_e32 v3, s58
	v_cndmask_b32_e32 v0, v0, v3, vcc
	v_mov_b32_e32 v3, s59
	v_cndmask_b32_e32 v1, v1, v3, vcc
	v_add_co_u32_e32 v0, vcc, v0, v163
	s_nop 1
	v_addc_co_u32_e32 v1, vcc, 0, v1, vcc
	global_load_dwordx4 v[120:123], v[0:1], off
	v_add_u32_e32 v163, 0x4000, v163
	v_add_u32_e32 v164, 32, v161
	v_cmp_gt_u32_e32 vcc, 0x1000, v164
	v_mov_b32_e32 v0, s98
	v_mov_b32_e32 v1, s99
	v_mov_b32_e32 v3, s58
	v_cndmask_b32_e32 v0, v0, v3, vcc
	v_mov_b32_e32 v3, s59
	v_cndmask_b32_e32 v1, v1, v3, vcc
	v_add_co_u32_e32 v0, vcc, v0, v163
	s_nop 1
	v_addc_co_u32_e32 v1, vcc, 0, v1, vcc
	global_load_dwordx4 v[124:127], v[0:1], off
	v_add_u32_e32 v163, 0x4000, v163
	v_add_u32_e32 v164, 36, v161
	v_cmp_gt_u32_e32 vcc, 0x1000, v164
	v_mov_b32_e32 v0, s98
	v_mov_b32_e32 v1, s99
	v_mov_b32_e32 v3, s58
	v_cndmask_b32_e32 v0, v0, v3, vcc
	v_mov_b32_e32 v3, s59
	v_cndmask_b32_e32 v1, v1, v3, vcc
	v_add_co_u32_e32 v0, vcc, v0, v163
	s_nop 1
	v_addc_co_u32_e32 v1, vcc, 0, v1, vcc
	global_load_dwordx4 v[128:131], v[0:1], off
	v_add_u32_e32 v163, 0x4000, v163
	v_add_u32_e32 v164, 40, v161
	v_cmp_gt_u32_e32 vcc, 0x1000, v164
	v_mov_b32_e32 v0, s98
	v_mov_b32_e32 v1, s99
	v_mov_b32_e32 v3, s58
	v_cndmask_b32_e32 v0, v0, v3, vcc
	v_mov_b32_e32 v3, s59
	v_cndmask_b32_e32 v1, v1, v3, vcc
	v_add_co_u32_e32 v0, vcc, v0, v163
	s_nop 1
	v_addc_co_u32_e32 v1, vcc, 0, v1, vcc
	global_load_dwordx4 v[132:135], v[0:1], off
	v_add_u32_e32 v163, 0x4000, v163
	v_add_u32_e32 v164, 44, v161
	v_cmp_gt_u32_e32 vcc, 0x1000, v164
	v_mov_b32_e32 v0, s98
	v_mov_b32_e32 v1, s99
	v_mov_b32_e32 v3, s58
	v_cndmask_b32_e32 v0, v0, v3, vcc
	v_mov_b32_e32 v3, s59
	v_cndmask_b32_e32 v1, v1, v3, vcc
	v_add_co_u32_e32 v0, vcc, v0, v163
	s_nop 1
	v_addc_co_u32_e32 v1, vcc, 0, v1, vcc
	global_load_dwordx4 v[136:139], v[0:1], off
	v_add_u32_e32 v163, 0x4000, v163
	v_add_u32_e32 v164, s4, v162
	global_load_dwordx4 v[4:7], v164, s[100:101]
	v_add_u32_e32 v164, s5, v162
	global_load_dwordx4 v[8:11], v164, s[100:101]
	ds_write_b32 v155, v44 offset:0
	ds_write_b32 v155, v45 offset:272
	ds_write_b32 v155, v46 offset:544
	ds_write_b32 v155, v47 offset:816
	ds_write_b32 v155, v48 offset:64
	ds_write_b32 v155, v49 offset:336
	ds_write_b32 v155, v50 offset:608
	ds_write_b32 v155, v51 offset:880
	ds_write_b32 v155, v52 offset:128
	ds_write_b32 v155, v53 offset:400
	ds_write_b32 v155, v54 offset:672
	ds_write_b32 v155, v55 offset:944
	ds_write_b32 v155, v56 offset:192
	ds_write_b32 v155, v57 offset:464
	ds_write_b32 v155, v58 offset:736
	ds_write_b32 v155, v59 offset:1008
	s_waitcnt lgkmcnt(0)
	ds_read_b128 v[16:19], v156 offset:0
	ds_read_b128 v[20:23], v156 offset:1088
	ds_read_b128 v[24:27], v156 offset:2176
	ds_read_b128 v[28:31], v156 offset:3264
	v_add_u32_e32 v164, 0, v161
	v_cmp_le_u32_e32 vcc, s7, v164
	s_waitcnt vmcnt(0)
	s_waitcnt lgkmcnt(3)
	v_cndmask_b32_e32 v12, v4, v8, vcc
	v_cndmask_b32_e32 v13, v5, v9, vcc
	v_cndmask_b32_e32 v14, v6, v10, vcc
	v_cndmask_b32_e32 v15, v7, v11, vcc
	v_fmac_f32_e32 v92, v12, v16
	v_fmac_f32_e32 v93, v13, v17
	v_fmac_f32_e32 v94, v14, v18
	v_fmac_f32_e32 v95, v15, v19
	global_store_dwordx4 v158, v[92:95], s[56:57]
	v_add_u32_e32 v158, 0x4000, v158
	v_add_u32_e32 v164, 4, v161
	v_cmp_le_u32_e32 vcc, s7, v164
	s_waitcnt vmcnt(1)
	s_waitcnt lgkmcnt(2)
	v_cndmask_b32_e32 v12, v4, v8, vcc
	v_cndmask_b32_e32 v13, v5, v9, vcc
	v_cndmask_b32_e32 v14, v6, v10, vcc
	v_cndmask_b32_e32 v15, v7, v11, vcc
	v_fmac_f32_e32 v96, v12, v20
	v_fmac_f32_e32 v97, v13, v21
	v_fmac_f32_e32 v98, v14, v22
	v_fmac_f32_e32 v99, v15, v23
	global_store_dwordx4 v158, v[96:99], s[56:57]
	v_add_u32_e32 v158, 0x4000, v158
	v_add_u32_e32 v164, 8, v161
	v_cmp_le_u32_e32 vcc, s7, v164
	s_waitcnt vmcnt(2)
	s_waitcnt lgkmcnt(1)
	v_cndmask_b32_e32 v12, v4, v8, vcc
	v_cndmask_b32_e32 v13, v5, v9, vcc
	v_cndmask_b32_e32 v14, v6, v10, vcc
	v_cndmask_b32_e32 v15, v7, v11, vcc
	v_fmac_f32_e32 v100, v12, v24
	v_fmac_f32_e32 v101, v13, v25
	v_fmac_f32_e32 v102, v14, v26
	v_fmac_f32_e32 v103, v15, v27
	global_store_dwordx4 v158, v[100:103], s[56:57]
	v_add_u32_e32 v158, 0x4000, v158
	v_add_u32_e32 v164, 12, v161
	v_cmp_le_u32_e32 vcc, s7, v164
	s_waitcnt vmcnt(3)
	s_waitcnt lgkmcnt(0)
	v_cndmask_b32_e32 v12, v4, v8, vcc
	v_cndmask_b32_e32 v13, v5, v9, vcc
	v_cndmask_b32_e32 v14, v6, v10, vcc
	v_cndmask_b32_e32 v15, v7, v11, vcc
	v_fmac_f32_e32 v104, v12, v28
	v_fmac_f32_e32 v105, v13, v29
	v_fmac_f32_e32 v106, v14, v30
	v_fmac_f32_e32 v107, v15, v31
	global_store_dwordx4 v158, v[104:107], s[56:57]
	v_add_u32_e32 v158, 0x4000, v158
	ds_write_b32 v155, v60 offset:0
	ds_write_b32 v155, v61 offset:272
	ds_write_b32 v155, v62 offset:544
	ds_write_b32 v155, v63 offset:816
	ds_write_b32 v155, v64 offset:64
	ds_write_b32 v155, v65 offset:336
	ds_write_b32 v155, v66 offset:608
	ds_write_b32 v155, v67 offset:880
	ds_write_b32 v155, v68 offset:128
	ds_write_b32 v155, v69 offset:400
	ds_write_b32 v155, v70 offset:672
	ds_write_b32 v155, v71 offset:944
	ds_write_b32 v155, v72 offset:192
	ds_write_b32 v155, v73 offset:464
	ds_write_b32 v155, v74 offset:736
	ds_write_b32 v155, v75 offset:1008
	s_waitcnt lgkmcnt(0)
	ds_read_b128 v[16:19], v156 offset:0
	ds_read_b128 v[20:23], v156 offset:1088
	ds_read_b128 v[24:27], v156 offset:2176
	ds_read_b128 v[28:31], v156 offset:3264
	v_add_u32_e32 v164, 16, v161
	v_cmp_le_u32_e32 vcc, s7, v164
	s_waitcnt vmcnt(4)
	s_waitcnt lgkmcnt(3)
	v_cndmask_b32_e32 v12, v4, v8, vcc
	v_cndmask_b32_e32 v13, v5, v9, vcc
	v_cndmask_b32_e32 v14, v6, v10, vcc
	v_cndmask_b32_e32 v15, v7, v11, vcc
	v_fmac_f32_e32 v108, v12, v16
	v_fmac_f32_e32 v109, v13, v17
	v_fmac_f32_e32 v110, v14, v18
	v_fmac_f32_e32 v111, v15, v19
	global_store_dwordx4 v158, v[108:111], s[56:57]
	v_add_u32_e32 v158, 0x4000, v158
	v_add_u32_e32 v164, 20, v161
	v_cmp_le_u32_e32 vcc, s7, v164
	s_waitcnt vmcnt(5)
	s_waitcnt lgkmcnt(2)
	v_cndmask_b32_e32 v12, v4, v8, vcc
	v_cndmask_b32_e32 v13, v5, v9, vcc
	v_cndmask_b32_e32 v14, v6, v10, vcc
	v_cndmask_b32_e32 v15, v7, v11, vcc
	v_fmac_f32_e32 v112, v12, v20
	v_fmac_f32_e32 v113, v13, v21
	v_fmac_f32_e32 v114, v14, v22
	v_fmac_f32_e32 v115, v15, v23
	global_store_dwordx4 v158, v[112:115], s[56:57]
	v_add_u32_e32 v158, 0x4000, v158
	v_add_u32_e32 v164, 24, v161
	v_cmp_le_u32_e32 vcc, s7, v164
	s_waitcnt vmcnt(6)
	s_waitcnt lgkmcnt(1)
	v_cndmask_b32_e32 v12, v4, v8, vcc
	v_cndmask_b32_e32 v13, v5, v9, vcc
	v_cndmask_b32_e32 v14, v6, v10, vcc
	v_cndmask_b32_e32 v15, v7, v11, vcc
	v_fmac_f32_e32 v116, v12, v24
	v_fmac_f32_e32 v117, v13, v25
	v_fmac_f32_e32 v118, v14, v26
	v_fmac_f32_e32 v119, v15, v27
	global_store_dwordx4 v158, v[116:119], s[56:57]
	v_add_u32_e32 v158, 0x4000, v158
	v_add_u32_e32 v164, 28, v161
	v_cmp_le_u32_e32 vcc, s7, v164
	s_waitcnt vmcnt(7)
	s_waitcnt lgkmcnt(0)
	v_cndmask_b32_e32 v12, v4, v8, vcc
	v_cndmask_b32_e32 v13, v5, v9, vcc
	v_cndmask_b32_e32 v14, v6, v10, vcc
	v_cndmask_b32_e32 v15, v7, v11, vcc
	v_fmac_f32_e32 v120, v12, v28
	v_fmac_f32_e32 v121, v13, v29
	v_fmac_f32_e32 v122, v14, v30
	v_fmac_f32_e32 v123, v15, v31
	global_store_dwordx4 v158, v[120:123], s[56:57]
	v_add_u32_e32 v158, 0x4000, v158
	ds_write_b32 v155, v76 offset:0
	ds_write_b32 v155, v77 offset:272
	ds_write_b32 v155, v78 offset:544
	ds_write_b32 v155, v79 offset:816
	ds_write_b32 v155, v80 offset:64
	ds_write_b32 v155, v81 offset:336
	ds_write_b32 v155, v82 offset:608
	ds_write_b32 v155, v83 offset:880
	ds_write_b32 v155, v84 offset:128
	ds_write_b32 v155, v85 offset:400
	ds_write_b32 v155, v86 offset:672
	ds_write_b32 v155, v87 offset:944
	ds_write_b32 v155, v88 offset:192
	ds_write_b32 v155, v89 offset:464
	ds_write_b32 v155, v90 offset:736
	ds_write_b32 v155, v91 offset:1008
	s_waitcnt lgkmcnt(0)
	ds_read_b128 v[16:19], v156 offset:0
	ds_read_b128 v[20:23], v156 offset:1088
	ds_read_b128 v[24:27], v156 offset:2176
	ds_read_b128 v[28:31], v156 offset:3264
	v_add_u32_e32 v164, 32, v161
	v_cmp_le_u32_e32 vcc, s7, v164
	s_waitcnt vmcnt(8)
	s_waitcnt lgkmcnt(3)
	v_cndmask_b32_e32 v12, v4, v8, vcc
	v_cndmask_b32_e32 v13, v5, v9, vcc
	v_cndmask_b32_e32 v14, v6, v10, vcc
	v_cndmask_b32_e32 v15, v7, v11, vcc
	v_fmac_f32_e32 v124, v12, v16
	v_fmac_f32_e32 v125, v13, v17
	v_fmac_f32_e32 v126, v14, v18
	v_fmac_f32_e32 v127, v15, v19
	global_store_dwordx4 v158, v[124:127], s[56:57]
	v_add_u32_e32 v158, 0x4000, v158
	v_add_u32_e32 v164, 36, v161
	v_cmp_le_u32_e32 vcc, s7, v164
	s_waitcnt vmcnt(9)
	s_waitcnt lgkmcnt(2)
	v_cndmask_b32_e32 v12, v4, v8, vcc
	v_cndmask_b32_e32 v13, v5, v9, vcc
	v_cndmask_b32_e32 v14, v6, v10, vcc
	v_cndmask_b32_e32 v15, v7, v11, vcc
	v_fmac_f32_e32 v128, v12, v20
	v_fmac_f32_e32 v129, v13, v21
	v_fmac_f32_e32 v130, v14, v22
	v_fmac_f32_e32 v131, v15, v23
	global_store_dwordx4 v158, v[128:131], s[56:57]
	v_add_u32_e32 v158, 0x4000, v158
	v_add_u32_e32 v164, 40, v161
	v_cmp_le_u32_e32 vcc, s7, v164
	s_waitcnt vmcnt(10)
	s_waitcnt lgkmcnt(1)
	v_cndmask_b32_e32 v12, v4, v8, vcc
	v_cndmask_b32_e32 v13, v5, v9, vcc
	v_cndmask_b32_e32 v14, v6, v10, vcc
	v_cndmask_b32_e32 v15, v7, v11, vcc
	v_fmac_f32_e32 v132, v12, v24
	v_fmac_f32_e32 v133, v13, v25
	v_fmac_f32_e32 v134, v14, v26
	v_fmac_f32_e32 v135, v15, v27
	global_store_dwordx4 v158, v[132:135], s[56:57]
	v_add_u32_e32 v158, 0x4000, v158
	v_add_u32_e32 v164, 44, v161
	v_cmp_le_u32_e32 vcc, s7, v164
	s_waitcnt vmcnt(11)
	s_waitcnt lgkmcnt(0)
	v_cndmask_b32_e32 v12, v4, v8, vcc
	v_cndmask_b32_e32 v13, v5, v9, vcc
	v_cndmask_b32_e32 v14, v6, v10, vcc
	v_cndmask_b32_e32 v15, v7, v11, vcc
	v_fmac_f32_e32 v136, v12, v28
	v_fmac_f32_e32 v137, v13, v29
	v_fmac_f32_e32 v138, v14, v30
	v_fmac_f32_e32 v139, v15, v31
	global_store_dwordx4 v158, v[136:139], s[56:57]
	v_add_u32_e32 v158, 0x4000, v158
	v_mov_b32_e32 v44, 0
	v_mov_b32_e32 v45, 0
	v_mov_b32_e32 v46, 0
	v_mov_b32_e32 v47, 0
	v_mov_b32_e32 v48, 0
	v_mov_b32_e32 v49, 0
	v_mov_b32_e32 v50, 0
	v_mov_b32_e32 v51, 0
	v_mov_b32_e32 v52, 0
	v_mov_b32_e32 v53, 0
	v_mov_b32_e32 v54, 0
	v_mov_b32_e32 v55, 0
	v_mov_b32_e32 v56, 0
	v_mov_b32_e32 v57, 0
	v_mov_b32_e32 v58, 0
	v_mov_b32_e32 v59, 0
	v_mov_b32_e32 v60, 0
	v_mov_b32_e32 v61, 0
	v_mov_b32_e32 v62, 0
	v_mov_b32_e32 v63, 0
	v_mov_b32_e32 v64, 0
	v_mov_b32_e32 v65, 0
	v_mov_b32_e32 v66, 0
	v_mov_b32_e32 v67, 0
	v_mov_b32_e32 v68, 0
	v_mov_b32_e32 v69, 0
	v_mov_b32_e32 v70, 0
	v_mov_b32_e32 v71, 0
	v_mov_b32_e32 v72, 0
	v_mov_b32_e32 v73, 0
	v_mov_b32_e32 v74, 0
	v_mov_b32_e32 v75, 0
	v_mov_b32_e32 v76, 0
	v_mov_b32_e32 v77, 0
	v_mov_b32_e32 v78, 0
	v_mov_b32_e32 v79, 0
	v_mov_b32_e32 v80, 0
	v_mov_b32_e32 v81, 0
	v_mov_b32_e32 v82, 0
	v_mov_b32_e32 v83, 0
	v_mov_b32_e32 v84, 0
	v_mov_b32_e32 v85, 0
	v_mov_b32_e32 v86, 0
	v_mov_b32_e32 v87, 0
	v_mov_b32_e32 v88, 0
	v_mov_b32_e32 v89, 0
	v_mov_b32_e32 v90, 0
	v_mov_b32_e32 v91, 0
	s_mov_b32 s34, 0
	s_add_u32 s35, s35, s52
	s_add_u32 s31, s31, 1
	s_cmp_ge_u32 s31, s30
	s_cbranch_scc1 .Lgm_f2_exit
	s_waitcnt vmcnt(17)
	s_branch .Lgm_f2_rot

.Lgm_wo_entry:
	s_add_u32 s56, s96, 0x7c84000
	s_addc_u32 s57, s97, 0
	s_mov_b32 s58, s16
	s_mov_b32 s59, s17
	s_sub_u32 s98, s30, 0x1000000
	s_subb_u32 s99, s31, 0
	s_mul_i32 s4, s36, 0x12000
	s_add_u32 s100, s96, 0x2e02000
	s_addc_u32 s101, s97, 0
	s_add_u32 s100, s100, s4
	s_addc_u32 s101, s101, 0
	s_mov_b32 s52, s61
	s_mov_b32 s53, s63
	s_movk_i32 s54, 0x100
	s_cmp_ge_u32 s53, s54
	s_cbranch_scc1 .Lgm_wo_exit
	s_mov_b32 s30, 0
	s_mov_b32 s4, s53
.Lgm_wo_cnt:
	s_add_u32 s30, s30, 16
	s_add_u32 s4, s4, s52
	s_cmp_lt_u32 s4, s54
	s_cbranch_scc1 .Lgm_wo_cnt
	s_add_u32 s48, s96, 0x7084000
	s_addc_u32 s49, s97, 0
	s_mul_i32 s4, s36, 0x200000
	s_add_u32 s50, s96, 0x980000
	s_addc_u32 s51, s97, 0
	s_add_u32 s50, s50, s4
	s_addc_u32 s51, s51, 0
	v_and_b32_e32 v0, 63, v206
	v_lshrrev_b32_e32 v1, 6, v206
	v_lshrrev_b32_e32 v3, 3, v0
	v_and_b32_e32 v4, 7, v0
	v_readfirstlane_b32 s42, v1
	v_xor_b32_e32 v4, v4, v3
	v_lshl_add_u32 v3, v1, 3, v3
	v_lshlrev_b32_e32 v3, 11, v3
	v_lshl_add_u32 v148, v4, 4, v3
	v_add_u32_e32 v149, 0x20000, v148
	v_add_u32_e32 v150, 0x40000, v148
	v_and_b32_e32 v5, 15, v0
	v_lshrrev_b32_e32 v6, 4, v0
	v_and_b32_e32 v7, 7, v5
	v_xor_b32_e32 v7, v7, v6
	v_lshlrev_b32_e32 v7, 4, v7
	v_lshrrev_b32_e32 v8, 1, v1
	v_and_b32_e32 v9, 1, v1
	v_mul_u32_u24_e32 v10, 48, v8
	v_add_u32_e32 v11, v10, v5
	v_lshl_add_u32 v151, v11, 7, v7
	v_xor_b32_e32 v152, 64, v151
	v_lshl_add_u32 v11, v9, 6, v5
	v_lshl_add_u32 v153, v11, 7, v7
	v_add_u32_e32 v153, 0x6000, v153
	v_xor_b32_e32 v154, 64, v153
	s_mul_i32 s5, s42, 4352
	s_mov_b32 s6, 0x1ec10
	s_cmp_lt_u32 s42, 4
	s_cselect_b32 s6, 0x1e000, s6
	s_add_u32 s5, s5, s6
	v_mul_u32_u24_e32 v11, 1088, v6
	v_lshl_add_u32 v11, v5, 2, v11
	v_add_u32_e32 v155, s5, v11
	v_mul_u32_u24_e32 v11, 272, v6
	v_lshl_add_u32 v11, v5, 4, v11
	v_add_u32_e32 v156, s5, v11
	v_add_u32_e32 v11, v10, v6
	v_lshlrev_b32_e32 v12, 6, v9
	v_lshl_add_u32 v12, v5, 2, v12
	s_mov_b32 s4, 0x1000
	v_mul_lo_u32 v13, v11, s4
	v_lshl_add_u32 v157, v12, 2, v13
	v_mov_b32_e32 v159, v11
	v_lshlrev_b32_e32 v160, 2, v12
	s_lshl_b32 s42, s42, 10
	v_mov_b32_e32 v44, 0
	v_mov_b32_e32 v45, 0
	v_mov_b32_e32 v46, 0
	v_mov_b32_e32 v47, 0
	v_mov_b32_e32 v48, 0
	v_mov_b32_e32 v49, 0
	v_mov_b32_e32 v50, 0
	v_mov_b32_e32 v51, 0
	v_mov_b32_e32 v52, 0
	v_mov_b32_e32 v53, 0
	v_mov_b32_e32 v54, 0
	v_mov_b32_e32 v55, 0
	v_mov_b32_e32 v56, 0
	v_mov_b32_e32 v57, 0
	v_mov_b32_e32 v58, 0
	v_mov_b32_e32 v59, 0
	v_mov_b32_e32 v60, 0
	v_mov_b32_e32 v61, 0
	v_mov_b32_e32 v62, 0
	v_mov_b32_e32 v63, 0
	v_mov_b32_e32 v64, 0
	v_mov_b32_e32 v65, 0
	v_mov_b32_e32 v66, 0
	v_mov_b32_e32 v67, 0
	v_mov_b32_e32 v68, 0
	v_mov_b32_e32 v69, 0
	v_mov_b32_e32 v70, 0
	v_mov_b32_e32 v71, 0
	v_mov_b32_e32 v72, 0
	v_mov_b32_e32 v73, 0
	v_mov_b32_e32 v74, 0
	v_mov_b32_e32 v75, 0
	v_mov_b32_e32 v76, 0
	v_mov_b32_e32 v77, 0
	v_mov_b32_e32 v78, 0
	v_mov_b32_e32 v79, 0
	v_mov_b32_e32 v80, 0
	v_mov_b32_e32 v81, 0
	v_mov_b32_e32 v82, 0
	v_mov_b32_e32 v83, 0
	v_mov_b32_e32 v84, 0
	v_mov_b32_e32 v85, 0
	v_mov_b32_e32 v86, 0
	v_mov_b32_e32 v87, 0
	v_mov_b32_e32 v88, 0
	v_mov_b32_e32 v89, 0
	v_mov_b32_e32 v90, 0
	v_mov_b32_e32 v91, 0
	s_mov_b32 s31, 0
	s_mov_b32 s34, 0
	s_mov_b32 s35, s53
	s_mov_b32 s38, s53
	s_mov_b32 s39, 0
	s_mov_b32 s40, 0
	s_mov_b32 s41, s42
	s_and_b32 s4, s38, 31
	s_mul_i32 s4, s4, 0x60000
	s_add_u32 s44, s48, s4
	s_addc_u32 s45, s49, 0
	s_lshr_b32 s4, s38, 5
	s_mul_i32 s4, s4, 0x40000
	s_add_u32 s46, s50, s4
	s_addc_u32 s47, s51, 0
	s_add_u32 m0, s41, 0x0
	s_nop 0
	global_load_lds_dwordx4 v148, s[44:45]
	s_add_u32 m0, s41, 0x2000
	s_nop 0
	global_load_lds_dwordx4 v149, s[44:45]
	s_add_u32 m0, s41, 0x4000
	s_nop 0
	global_load_lds_dwordx4 v150, s[44:45]
	s_add_u32 m0, s41, 0x6000
	s_nop 0
	global_load_lds_dwordx4 v148, s[46:47]
	s_add_u32 m0, s41, 0x8000
	s_nop 0
	global_load_lds_dwordx4 v149, s[46:47]
	s_add_u32 s39, s39, 1
	s_add_u32 s44, s44, 0x80
	s_addc_u32 s45, s45, 0
	s_add_u32 s46, s46, 0x80
	s_addc_u32 s47, s47, 0
	s_cmp_lt_u32 s39, 16
	s_cbranch_scc1 .Lgm_wo_dadv1
	s_mov_b32 s39, 0
	s_add_u32 s4, s38, s52
	s_cmp_lt_u32 s4, s54
	s_cselect_b32 s38, s4, s38
	s_and_b32 s4, s38, 31
	s_mul_i32 s4, s4, 0x60000
	s_add_u32 s44, s48, s4
	s_addc_u32 s45, s49, 0
	s_lshr_b32 s4, s38, 5
	s_mul_i32 s4, s4, 0x40000
	s_add_u32 s46, s50, s4
	s_addc_u32 s47, s51, 0

.Lgm_wo_dadv3:
	ds_read_b128 v[120:123], v152 offset:0
	ds_read_b128 v[124:127], v152 offset:2048
	ds_read_b128 v[128:131], v152 offset:4096
	ds_read_b128 v[132:135], v154 offset:0
	ds_read_b128 v[136:139], v154 offset:2048
	ds_read_b128 v[140:143], v154 offset:4096
	ds_read_b128 v[144:147], v154 offset:6144
	s_waitcnt lgkmcnt(10)
	v_mfma_f32_16x16x32_bf16 v[44:47], v[92:95], v[104:107], v[44:47]
	v_mfma_f32_16x16x32_bf16 v[60:63], v[96:99], v[104:107], v[60:63]
	v_mfma_f32_16x16x32_bf16 v[76:79], v[100:103], v[104:107], v[76:79]
	s_waitcnt lgkmcnt(9)
	v_mfma_f32_16x16x32_bf16 v[48:51], v[92:95], v[108:111], v[48:51]
	v_mfma_f32_16x16x32_bf16 v[64:67], v[96:99], v[108:111], v[64:67]
	v_mfma_f32_16x16x32_bf16 v[80:83], v[100:103], v[108:111], v[80:83]
	s_waitcnt lgkmcnt(8)
	v_mfma_f32_16x16x32_bf16 v[52:55], v[92:95], v[112:115], v[52:55]
	v_mfma_f32_16x16x32_bf16 v[68:71], v[96:99], v[112:115], v[68:71]
	v_mfma_f32_16x16x32_bf16 v[84:87], v[100:103], v[112:115], v[84:87]
	s_waitcnt lgkmcnt(7)
	v_mfma_f32_16x16x32_bf16 v[56:59], v[92:95], v[116:119], v[56:59]
	v_mfma_f32_16x16x32_bf16 v[72:75], v[96:99], v[116:119], v[72:75]
	v_mfma_f32_16x16x32_bf16 v[88:91], v[100:103], v[116:119], v[88:91]
	s_waitcnt lgkmcnt(0)
	s_add_u32 s34, s34, 1
	s_cmp_lt_u32 s34, 16
	s_cbranch_scc1 .Lgm_wo_next
	v_mfma_f32_16x16x32_bf16 v[44:47], v[120:123], v[132:135], v[44:47]
	v_mfma_f32_16x16x32_bf16 v[60:63], v[124:127], v[132:135], v[60:63]
	v_mfma_f32_16x16x32_bf16 v[76:79], v[128:131], v[132:135], v[76:79]
	v_mfma_f32_16x16x32_bf16 v[48:51], v[120:123], v[136:139], v[48:51]
	v_mfma_f32_16x16x32_bf16 v[64:67], v[124:127], v[136:139], v[64:67]
	v_mfma_f32_16x16x32_bf16 v[80:83], v[128:131], v[136:139], v[80:83]
	v_mfma_f32_16x16x32_bf16 v[52:55], v[120:123], v[140:143], v[52:55]
	v_mfma_f32_16x16x32_bf16 v[68:71], v[124:127], v[140:143], v[68:71]
	v_mfma_f32_16x16x32_bf16 v[84:87], v[128:131], v[140:143], v[84:87]
	v_mfma_f32_16x16x32_bf16 v[56:59], v[120:123], v[144:147], v[56:59]
	v_mfma_f32_16x16x32_bf16 v[72:75], v[124:127], v[144:147], v[72:75]
	v_mfma_f32_16x16x32_bf16 v[88:91], v[128:131], v[144:147], v[88:91]
	s_and_b32 s6, s35, 31
	s_mul_i32 s6, s6, 192
	s_lshr_b32 s7, s35, 5
	s_lshl_b32 s7, s7, 7
	s_nop 7
	s_mul_i32 s4, s6, 0x1000
	s_lshl_b32 s5, s7, 2
	s_add_u32 s4, s4, s5
	v_add_u32_e32 v158, s4, v157
	v_add_u32_e32 v161, s6, v159
	v_lshl_add_u32 v162, s7, 2, v160
	s_sub_i32 s4, s6, 0xc00
	s_max_i32 s4, s4, 0
	s_lshr_b32 s4, s4, 10
	s_add_i32 s5, s6, -2881
	s_max_i32 s5, s5, 0
	s_lshr_b32 s5, s5, 10
	s_movk_i32 s7, 0x1400
	s_cmp_eq_u32 s4, 0
	s_cselect_b32 s7, 0x1000, s7
	s_mul_i32 s4, s4, 0x6000
	s_mul_i32 s5, s5, 0x6000
	v_mov_b32_e32 v163, v158
	v_add_u32_e32 v164, 0, v161
	v_cmp_gt_u32_e32 vcc, 0x1000, v164
	v_mov_b32_e32 v0, s98
	v_mov_b32_e32 v1, s99
	v_mov_b32_e32 v3, s58
	v_cndmask_b32_e32 v0, v0, v3, vcc
	v_mov_b32_e32 v3, s59
	v_cndmask_b32_e32 v1, v1, v3, vcc
	v_add_co_u32_e32 v0, vcc, v0, v163
	s_nop 1
	v_addc_co_u32_e32 v1, vcc, 0, v1, vcc
	global_load_dwordx4 v[92:95], v[0:1], off
	v_add_u32_e32 v163, 0x4000, v163
	v_add_u32_e32 v164, 4, v161
	v_cmp_gt_u32_e32 vcc, 0x1000, v164
	v_mov_b32_e32 v0, s98
	v_mov_b32_e32 v1, s99
	v_mov_b32_e32 v3, s58
	v_cndmask_b32_e32 v0, v0, v3, vcc
	v_mov_b32_e32 v3, s59
	v_cndmask_b32_e32 v1, v1, v3, vcc
	v_add_co_u32_e32 v0, vcc, v0, v163
	s_nop 1
	v_addc_co_u32_e32 v1, vcc, 0, v1, vcc
	global_load_dwordx4 v[96:99], v[0:1], off
	v_add_u32_e32 v163, 0x4000, v163
	v_add_u32_e32 v164, 8, v161
	v_cmp_gt_u32_e32 vcc, 0x1000, v164
	v_mov_b32_e32 v0, s98
	v_mov_b32_e32 v1, s99
	v_mov_b32_e32 v3, s58
	v_cndmask_b32_e32 v0, v0, v3, vcc
	v_mov_b32_e32 v3, s59
	v_cndmask_b32_e32 v1, v1, v3, vcc
	v_add_co_u32_e32 v0, vcc, v0, v163
	s_nop 1
	v_addc_co_u32_e32 v1, vcc, 0, v1, vcc
	global_load_dwordx4 v[100:103], v[0:1], off
	v_add_u32_e32 v163, 0x4000, v163
	v_add_u32_e32 v164, 12, v161
	v_cmp_gt_u32_e32 vcc, 0x1000, v164
	v_mov_b32_e32 v0, s98
	v_mov_b32_e32 v1, s99
	v_mov_b32_e32 v3, s58
	v_cndmask_b32_e32 v0, v0, v3, vcc
	v_mov_b32_e32 v3, s59
	v_cndmask_b32_e32 v1, v1, v3, vcc
	v_add_co_u32_e32 v0, vcc, v0, v163
	s_nop 1
	v_addc_co_u32_e32 v1, vcc, 0, v1, vcc
	global_load_dwordx4 v[104:107], v[0:1], off
	v_add_u32_e32 v163, 0x4000, v163
	v_add_u32_e32 v164, 16, v161
	v_cmp_gt_u32_e32 vcc, 0x1000, v164
	v_mov_b32_e32 v0, s98
	v_mov_b32_e32 v1, s99
	v_mov_b32_e32 v3, s58
	v_cndmask_b32_e32 v0, v0, v3, vcc
	v_mov_b32_e32 v3, s59
	v_cndmask_b32_e32 v1, v1, v3, vcc
	v_add_co_u32_e32 v0, vcc, v0, v163
	s_nop 1
	v_addc_co_u32_e32 v1, vcc, 0, v1, vcc
	global_load_dwordx4 v[108:111], v[0:1], off
	v_add_u32_e32 v163, 0x4000, v163
	v_add_u32_e32 v164, 20, v161
	v_cmp_gt_u32_e32 vcc, 0x1000, v164
	v_mov_b32_e32 v0, s98
	v_mov_b32_e32 v1, s99
	v_mov_b32_e32 v3, s58
	v_cndmask_b32_e32 v0, v0, v3, vcc
	v_mov_b32_e32 v3, s59
	v_cndmask_b32_e32 v1, v1, v3, vcc
	v_add_co_u32_e32 v0, vcc, v0, v163
	s_nop 1
	v_addc_co_u32_e32 v1, vcc, 0, v1, vcc
	global_load_dwordx4 v[112:115], v[0:1], off
	v_add_u32_e32 v163, 0x4000, v163
	v_add_u32_e32 v164, 24, v161
	v_cmp_gt_u32_e32 vcc, 0x1000, v164
	v_mov_b32_e32 v0, s98
	v_mov_b32_e32 v1, s99
	v_mov_b32_e32 v3, s58
	v_cndmask_b32_e32 v0, v0, v3, vcc
	v_mov_b32_e32 v3, s59
	v_cndmask_b32_e32 v1, v1, v3, vcc
	v_add_co_u32_e32 v0, vcc, v0, v163
	s_nop 1
	v_addc_co_u32_e32 v1, vcc, 0, v1, vcc
	global_load_dwordx4 v[116:119], v[0:1], off
	v_add_u32_e32 v163, 0x4000, v163
	v_add_u32_e32 v164, 28, v161
	v_cmp_gt_u32_e32 vcc, 0x1000, v164
	v_mov_b32_e32 v0, s98
	v_mov_b32_e32 v1, s99
	v_mov_b32_e32 v3, s58
	v_cndmask_b32_e32 v0, v0, v3, vcc
	v_mov_b32_e32 v3, s59
	v_cndmask_b32_e32 v1, v1, v3, vcc
	v_add_co_u32_e32 v0, vcc, v0, v163
	s_nop 1
	v_addc_co_u32_e32 v1, vcc, 0, v1, vcc
	global_load_dwordx4 v[120:123], v[0:1], off
	v_add_u32_e32 v163, 0x4000, v163
	v_add_u32_e32 v164, 32, v161
	v_cmp_gt_u32_e32 vcc, 0x1000, v164
	v_mov_b32_e32 v0, s98
	v_mov_b32_e32 v1, s99
	v_mov_b32_e32 v3, s58
	v_cndmask_b32_e32 v0, v0, v3, vcc
	v_mov_b32_e32 v3, s59
	v_cndmask_b32_e32 v1, v1, v3, vcc
	v_add_co_u32_e32 v0, vcc, v0, v163
	s_nop 1
	v_addc_co_u32_e32 v1, vcc, 0, v1, vcc
	global_load_dwordx4 v[124:127], v[0:1], off
	v_add_u32_e32 v163, 0x4000, v163
	v_add_u32_e32 v164, 36, v161
	v_cmp_gt_u32_e32 vcc, 0x1000, v164
	v_mov_b32_e32 v0, s98
	v_mov_b32_e32 v1, s99
	v_mov_b32_e32 v3, s58
	v_cndmask_b32_e32 v0, v0, v3, vcc
	v_mov_b32_e32 v3, s59
	v_cndmask_b32_e32 v1, v1, v3, vcc
	v_add_co_u32_e32 v0, vcc, v0, v163
	s_nop 1
	v_addc_co_u32_e32 v1, vcc, 0, v1, vcc
	global_load_dwordx4 v[128:131], v[0:1], off
	v_add_u32_e32 v163, 0x4000, v163
	v_add_u32_e32 v164, 40, v161
	v_cmp_gt_u32_e32 vcc, 0x1000, v164
	v_mov_b32_e32 v0, s98
	v_mov_b32_e32 v1, s99
	v_mov_b32_e32 v3, s58
	v_cndmask_b32_e32 v0, v0, v3, vcc
	v_mov_b32_e32 v3, s59
	v_cndmask_b32_e32 v1, v1, v3, vcc
	v_add_co_u32_e32 v0, vcc, v0, v163
	s_nop 1
	v_addc_co_u32_e32 v1, vcc, 0, v1, vcc
	global_load_dwordx4 v[132:135], v[0:1], off
	v_add_u32_e32 v163, 0x4000, v163
	v_add_u32_e32 v164, 44, v161
	v_cmp_gt_u32_e32 vcc, 0x1000, v164
	v_mov_b32_e32 v0, s98
	v_mov_b32_e32 v1, s99
	v_mov_b32_e32 v3, s58
	v_cndmask_b32_e32 v0, v0, v3, vcc
	v_mov_b32_e32 v3, s59
	v_cndmask_b32_e32 v1, v1, v3, vcc
	v_add_co_u32_e32 v0, vcc, v0, v163
	s_nop 1
	v_addc_co_u32_e32 v1, vcc, 0, v1, vcc
	global_load_dwordx4 v[136:139], v[0:1], off
	v_add_u32_e32 v163, 0x4000, v163
	v_add_u32_e32 v164, s4, v162
	global_load_dwordx4 v[4:7], v164, s[100:101]
	v_add_u32_e32 v164, s5, v162
	global_load_dwordx4 v[8:11], v164, s[100:101]
	ds_write_b32 v155, v44 offset:0
	ds_write_b32 v155, v45 offset:272
	ds_write_b32 v155, v46 offset:544
	ds_write_b32 v155, v47 offset:816
	ds_write_b32 v155, v48 offset:64
	ds_write_b32 v155, v49 offset:336
	ds_write_b32 v155, v50 offset:608
	ds_write_b32 v155, v51 offset:880
	ds_write_b32 v155, v52 offset:128
	ds_write_b32 v155, v53 offset:400
	ds_write_b32 v155, v54 offset:672
	ds_write_b32 v155, v55 offset:944
	ds_write_b32 v155, v56 offset:192
	ds_write_b32 v155, v57 offset:464
	ds_write_b32 v155, v58 offset:736
	ds_write_b32 v155, v59 offset:1008
	s_waitcnt lgkmcnt(0)
	ds_read_b128 v[16:19], v156 offset:0
	ds_read_b128 v[20:23], v156 offset:1088
	ds_read_b128 v[24:27], v156 offset:2176
	ds_read_b128 v[28:31], v156 offset:3264
	v_add_u32_e32 v164, 0, v161
	v_cmp_le_u32_e32 vcc, s7, v164
	s_waitcnt vmcnt(0)
	s_waitcnt lgkmcnt(3)
	v_cndmask_b32_e32 v12, v4, v8, vcc
	v_cndmask_b32_e32 v13, v5, v9, vcc
	v_cndmask_b32_e32 v14, v6, v10, vcc
	v_cndmask_b32_e32 v15, v7, v11, vcc
	v_fmac_f32_e32 v92, v12, v16
	v_fmac_f32_e32 v93, v13, v17
	v_fmac_f32_e32 v94, v14, v18
	v_fmac_f32_e32 v95, v15, v19
	global_store_dwordx4 v158, v[92:95], s[56:57]
	v_add_u32_e32 v158, 0x4000, v158
	v_add_u32_e32 v164, 4, v161
	v_cmp_le_u32_e32 vcc, s7, v164
	s_waitcnt vmcnt(1)
	s_waitcnt lgkmcnt(2)
	v_cndmask_b32_e32 v12, v4, v8, vcc
	v_cndmask_b32_e32 v13, v5, v9, vcc
	v_cndmask_b32_e32 v14, v6, v10, vcc
	v_cndmask_b32_e32 v15, v7, v11, vcc
	v_fmac_f32_e32 v96, v12, v20
	v_fmac_f32_e32 v97, v13, v21
	v_fmac_f32_e32 v98, v14, v22
	v_fmac_f32_e32 v99, v15, v23
	global_store_dwordx4 v158, v[96:99], s[56:57]
	v_add_u32_e32 v158, 0x4000, v158
	v_add_u32_e32 v164, 8, v161
	v_cmp_le_u32_e32 vcc, s7, v164
	s_waitcnt vmcnt(2)
	s_waitcnt lgkmcnt(1)
	v_cndmask_b32_e32 v12, v4, v8, vcc
	v_cndmask_b32_e32 v13, v5, v9, vcc
	v_cndmask_b32_e32 v14, v6, v10, vcc
	v_cndmask_b32_e32 v15, v7, v11, vcc
	v_fmac_f32_e32 v100, v12, v24
	v_fmac_f32_e32 v101, v13, v25
	v_fmac_f32_e32 v102, v14, v26
	v_fmac_f32_e32 v103, v15, v27
	global_store_dwordx4 v158, v[100:103], s[56:57]
	v_add_u32_e32 v158, 0x4000, v158
	v_add_u32_e32 v164, 12, v161
	v_cmp_le_u32_e32 vcc, s7, v164
	s_waitcnt vmcnt(3)
	s_waitcnt lgkmcnt(0)
	v_cndmask_b32_e32 v12, v4, v8, vcc
	v_cndmask_b32_e32 v13, v5, v9, vcc
	v_cndmask_b32_e32 v14, v6, v10, vcc
	v_cndmask_b32_e32 v15, v7, v11, vcc
	v_fmac_f32_e32 v104, v12, v28
	v_fmac_f32_e32 v105, v13, v29
	v_fmac_f32_e32 v106, v14, v30
	v_fmac_f32_e32 v107, v15, v31
	global_store_dwordx4 v158, v[104:107], s[56:57]
	v_add_u32_e32 v158, 0x4000, v158
	ds_write_b32 v155, v60 offset:0
	ds_write_b32 v155, v61 offset:272
	ds_write_b32 v155, v62 offset:544
	ds_write_b32 v155, v63 offset:816
	ds_write_b32 v155, v64 offset:64
	ds_write_b32 v155, v65 offset:336
	ds_write_b32 v155, v66 offset:608
	ds_write_b32 v155, v67 offset:880
	ds_write_b32 v155, v68 offset:128
	ds_write_b32 v155, v69 offset:400
	ds_write_b32 v155, v70 offset:672
	ds_write_b32 v155, v71 offset:944
	ds_write_b32 v155, v72 offset:192
	ds_write_b32 v155, v73 offset:464
	ds_write_b32 v155, v74 offset:736
	ds_write_b32 v155, v75 offset:1008
	s_waitcnt lgkmcnt(0)
	ds_read_b128 v[16:19], v156 offset:0
	ds_read_b128 v[20:23], v156 offset:1088
	ds_read_b128 v[24:27], v156 offset:2176
	ds_read_b128 v[28:31], v156 offset:3264
	v_add_u32_e32 v164, 16, v161
	v_cmp_le_u32_e32 vcc, s7, v164
	s_waitcnt vmcnt(4)
	s_waitcnt lgkmcnt(3)
	v_cndmask_b32_e32 v12, v4, v8, vcc
	v_cndmask_b32_e32 v13, v5, v9, vcc
	v_cndmask_b32_e32 v14, v6, v10, vcc
	v_cndmask_b32_e32 v15, v7, v11, vcc
	v_fmac_f32_e32 v108, v12, v16
	v_fmac_f32_e32 v109, v13, v17
	v_fmac_f32_e32 v110, v14, v18
	v_fmac_f32_e32 v111, v15, v19
	global_store_dwordx4 v158, v[108:111], s[56:57]
	v_add_u32_e32 v158, 0x4000, v158
	v_add_u32_e32 v164, 20, v161
	v_cmp_le_u32_e32 vcc, s7, v164
	s_waitcnt vmcnt(5)
	s_waitcnt lgkmcnt(2)
	v_cndmask_b32_e32 v12, v4, v8, vcc
	v_cndmask_b32_e32 v13, v5, v9, vcc
	v_cndmask_b32_e32 v14, v6, v10, vcc
	v_cndmask_b32_e32 v15, v7, v11, vcc
	v_fmac_f32_e32 v112, v12, v20
	v_fmac_f32_e32 v113, v13, v21
	v_fmac_f32_e32 v114, v14, v22
	v_fmac_f32_e32 v115, v15, v23
	global_store_dwordx4 v158, v[112:115], s[56:57]
	v_add_u32_e32 v158, 0x4000, v158
	v_add_u32_e32 v164, 24, v161
	v_cmp_le_u32_e32 vcc, s7, v164
	s_waitcnt vmcnt(6)
	s_waitcnt lgkmcnt(1)
	v_cndmask_b32_e32 v12, v4, v8, vcc
	v_cndmask_b32_e32 v13, v5, v9, vcc
	v_cndmask_b32_e32 v14, v6, v10, vcc
	v_cndmask_b32_e32 v15, v7, v11, vcc
	v_fmac_f32_e32 v116, v12, v24
	v_fmac_f32_e32 v117, v13, v25
	v_fmac_f32_e32 v118, v14, v26
	v_fmac_f32_e32 v119, v15, v27
	global_store_dwordx4 v158, v[116:119], s[56:57]
	v_add_u32_e32 v158, 0x4000, v158
	v_add_u32_e32 v164, 28, v161
	v_cmp_le_u32_e32 vcc, s7, v164
	s_waitcnt vmcnt(7)
	s_waitcnt lgkmcnt(0)
	v_cndmask_b32_e32 v12, v4, v8, vcc
	v_cndmask_b32_e32 v13, v5, v9, vcc
	v_cndmask_b32_e32 v14, v6, v10, vcc
	v_cndmask_b32_e32 v15, v7, v11, vcc
	v_fmac_f32_e32 v120, v12, v28
	v_fmac_f32_e32 v121, v13, v29
	v_fmac_f32_e32 v122, v14, v30
	v_fmac_f32_e32 v123, v15, v31
	global_store_dwordx4 v158, v[120:123], s[56:57]
	v_add_u32_e32 v158, 0x4000, v158
	ds_write_b32 v155, v76 offset:0
	ds_write_b32 v155, v77 offset:272
	ds_write_b32 v155, v78 offset:544
	ds_write_b32 v155, v79 offset:816
	ds_write_b32 v155, v80 offset:64
	ds_write_b32 v155, v81 offset:336
	ds_write_b32 v155, v82 offset:608
	ds_write_b32 v155, v83 offset:880
	ds_write_b32 v155, v84 offset:128
	ds_write_b32 v155, v85 offset:400
	ds_write_b32 v155, v86 offset:672
	ds_write_b32 v155, v87 offset:944
	ds_write_b32 v155, v88 offset:192
	ds_write_b32 v155, v89 offset:464
	ds_write_b32 v155, v90 offset:736
	ds_write_b32 v155, v91 offset:1008
	s_waitcnt lgkmcnt(0)
	ds_read_b128 v[16:19], v156 offset:0
	ds_read_b128 v[20:23], v156 offset:1088
	ds_read_b128 v[24:27], v156 offset:2176
	ds_read_b128 v[28:31], v156 offset:3264
	v_add_u32_e32 v164, 32, v161
	v_cmp_le_u32_e32 vcc, s7, v164
	s_waitcnt vmcnt(8)
	s_waitcnt lgkmcnt(3)
	v_cndmask_b32_e32 v12, v4, v8, vcc
	v_cndmask_b32_e32 v13, v5, v9, vcc
	v_cndmask_b32_e32 v14, v6, v10, vcc
	v_cndmask_b32_e32 v15, v7, v11, vcc
	v_fmac_f32_e32 v124, v12, v16
	v_fmac_f32_e32 v125, v13, v17
	v_fmac_f32_e32 v126, v14, v18
	v_fmac_f32_e32 v127, v15, v19
	global_store_dwordx4 v158, v[124:127], s[56:57]
	v_add_u32_e32 v158, 0x4000, v158
	v_add_u32_e32 v164, 36, v161
	v_cmp_le_u32_e32 vcc, s7, v164
	s_waitcnt vmcnt(9)
	s_waitcnt lgkmcnt(2)
	v_cndmask_b32_e32 v12, v4, v8, vcc
	v_cndmask_b32_e32 v13, v5, v9, vcc
	v_cndmask_b32_e32 v14, v6, v10, vcc
	v_cndmask_b32_e32 v15, v7, v11, vcc
	v_fmac_f32_e32 v128, v12, v20
	v_fmac_f32_e32 v129, v13, v21
	v_fmac_f32_e32 v130, v14, v22
	v_fmac_f32_e32 v131, v15, v23
	global_store_dwordx4 v158, v[128:131], s[56:57]
	v_add_u32_e32 v158, 0x4000, v158
	v_add_u32_e32 v164, 40, v161
	v_cmp_le_u32_e32 vcc, s7, v164
	s_waitcnt vmcnt(10)
	s_waitcnt lgkmcnt(1)
	v_cndmask_b32_e32 v12, v4, v8, vcc
	v_cndmask_b32_e32 v13, v5, v9, vcc
	v_cndmask_b32_e32 v14, v6, v10, vcc
	v_cndmask_b32_e32 v15, v7, v11, vcc
	v_fmac_f32_e32 v132, v12, v24
	v_fmac_f32_e32 v133, v13, v25
	v_fmac_f32_e32 v134, v14, v26
	v_fmac_f32_e32 v135, v15, v27
	global_store_dwordx4 v158, v[132:135], s[56:57]
	v_add_u32_e32 v158, 0x4000, v158
	v_add_u32_e32 v164, 44, v161
	v_cmp_le_u32_e32 vcc, s7, v164
	s_waitcnt vmcnt(11)
	s_waitcnt lgkmcnt(0)
	v_cndmask_b32_e32 v12, v4, v8, vcc
	v_cndmask_b32_e32 v13, v5, v9, vcc
	v_cndmask_b32_e32 v14, v6, v10, vcc
	v_cndmask_b32_e32 v15, v7, v11, vcc
	v_fmac_f32_e32 v136, v12, v28
	v_fmac_f32_e32 v137, v13, v29
	v_fmac_f32_e32 v138, v14, v30
	v_fmac_f32_e32 v139, v15, v31
	global_store_dwordx4 v158, v[136:139], s[56:57]
	v_add_u32_e32 v158, 0x4000, v158
	v_mov_b32_e32 v44, 0
	v_mov_b32_e32 v45, 0
	v_mov_b32_e32 v46, 0
	v_mov_b32_e32 v47, 0
	v_mov_b32_e32 v48, 0
	v_mov_b32_e32 v49, 0
	v_mov_b32_e32 v50, 0
	v_mov_b32_e32 v51, 0
	v_mov_b32_e32 v52, 0
	v_mov_b32_e32 v53, 0
	v_mov_b32_e32 v54, 0
	v_mov_b32_e32 v55, 0
	v_mov_b32_e32 v56, 0
	v_mov_b32_e32 v57, 0
	v_mov_b32_e32 v58, 0
	v_mov_b32_e32 v59, 0
	v_mov_b32_e32 v60, 0
	v_mov_b32_e32 v61, 0
	v_mov_b32_e32 v62, 0
	v_mov_b32_e32 v63, 0
	v_mov_b32_e32 v64, 0
	v_mov_b32_e32 v65, 0
	v_mov_b32_e32 v66, 0
	v_mov_b32_e32 v67, 0
	v_mov_b32_e32 v68, 0
	v_mov_b32_e32 v69, 0
	v_mov_b32_e32 v70, 0
	v_mov_b32_e32 v71, 0
	v_mov_b32_e32 v72, 0
	v_mov_b32_e32 v73, 0
	v_mov_b32_e32 v74, 0
	v_mov_b32_e32 v75, 0
	v_mov_b32_e32 v76, 0
	v_mov_b32_e32 v77, 0
	v_mov_b32_e32 v78, 0
	v_mov_b32_e32 v79, 0
	v_mov_b32_e32 v80, 0
	v_mov_b32_e32 v81, 0
	v_mov_b32_e32 v82, 0
	v_mov_b32_e32 v83, 0
	v_mov_b32_e32 v84, 0
	v_mov_b32_e32 v85, 0
	v_mov_b32_e32 v86, 0
	v_mov_b32_e32 v87, 0
	v_mov_b32_e32 v88, 0
	v_mov_b32_e32 v89, 0
	v_mov_b32_e32 v90, 0
	v_mov_b32_e32 v91, 0
	s_mov_b32 s34, 0
	s_add_u32 s35, s35, s52
	s_add_u32 s31, s31, 1
	s_cmp_ge_u32 s31, s30
	s_cbranch_scc1 .Lgm_wo_exit
	s_waitcnt vmcnt(17)
	s_branch .Lgm_wo_rot

.Lgm_wi_entry:
	s_add_u32 s56, s96, 0x3a24000
	s_addc_u32 s57, s97, 0
	s_mov_b32 s52, s61
	s_mov_b32 s53, s63
	s_movk_i32 s54, 0x260
	s_cmp_ge_u32 s53, s54
	s_cbranch_scc1 .Lgm_wi_exit
	s_mov_b32 s30, 0
	s_mov_b32 s4, s53
.Lgm_wi_cnt:
	s_add_u32 s30, s30, 16
	s_add_u32 s4, s4, s52
	s_cmp_lt_u32 s4, s54
	s_cbranch_scc1 .Lgm_wi_cnt
	s_add_u32 s48, s96, 0x2e24000
	s_addc_u32 s49, s97, 0
	s_mul_i32 s4, s36, 0x4c0000
	s_add_u32 s50, s96, 0x0
	s_addc_u32 s51, s97, 0
	s_add_u32 s50, s50, s4
	s_addc_u32 s51, s51, 0
	v_and_b32_e32 v0, 63, v206
	v_lshrrev_b32_e32 v1, 6, v206
	v_lshrrev_b32_e32 v3, 3, v0
	v_and_b32_e32 v4, 7, v0
	v_readfirstlane_b32 s42, v1
	v_xor_b32_e32 v4, v4, v3
	v_lshl_add_u32 v3, v1, 3, v3
	v_lshlrev_b32_e32 v3, 11, v3
	v_lshl_add_u32 v148, v4, 4, v3
	v_add_u32_e32 v149, 0x20000, v148
	v_add_u32_e32 v150, 0x40000, v148
	v_and_b32_e32 v5, 15, v0
	v_lshrrev_b32_e32 v6, 4, v0
	v_and_b32_e32 v7, 7, v5
	v_xor_b32_e32 v7, v7, v6
	v_lshlrev_b32_e32 v7, 4, v7
	v_lshrrev_b32_e32 v8, 1, v1
	v_and_b32_e32 v9, 1, v1
	v_mul_u32_u24_e32 v10, 48, v8
	v_add_u32_e32 v11, v10, v5
	v_lshl_add_u32 v151, v11, 7, v7
	v_xor_b32_e32 v152, 64, v151
	v_lshl_add_u32 v11, v9, 6, v5
	v_lshl_add_u32 v153, v11, 7, v7
	v_add_u32_e32 v153, 0x6000, v153
	v_xor_b32_e32 v154, 64, v153
	s_mul_i32 s5, s42, 4352
	s_mov_b32 s6, 0x1ec10
	s_cmp_lt_u32 s42, 4
	s_cselect_b32 s6, 0x1e000, s6
	s_add_u32 s5, s5, s6
	v_mul_u32_u24_e32 v11, 1088, v6
	v_lshl_add_u32 v11, v5, 2, v11
	v_add_u32_e32 v155, s5, v11
	v_mul_u32_u24_e32 v11, 272, v6
	v_lshl_add_u32 v11, v5, 4, v11
	v_add_u32_e32 v156, s5, v11
	v_add_u32_e32 v11, v10, v6
	v_lshlrev_b32_e32 v12, 6, v9
	v_lshl_add_u32 v12, v5, 2, v12
	s_mov_b32 s4, 0x2440
	v_mul_lo_u32 v13, v11, s4
	v_lshl_add_u32 v157, v12, 2, v13
	v_mov_b32_e32 v159, v12
	s_lshl_b32 s42, s42, 10
	v_mov_b32_e32 v44, 0
	v_mov_b32_e32 v45, 0
	v_mov_b32_e32 v46, 0
	v_mov_b32_e32 v47, 0
	v_mov_b32_e32 v48, 0
	v_mov_b32_e32 v49, 0
	v_mov_b32_e32 v50, 0
	v_mov_b32_e32 v51, 0
	v_mov_b32_e32 v52, 0
	v_mov_b32_e32 v53, 0
	v_mov_b32_e32 v54, 0
	v_mov_b32_e32 v55, 0
	v_mov_b32_e32 v56, 0
	v_mov_b32_e32 v57, 0
	v_mov_b32_e32 v58, 0
	v_mov_b32_e32 v59, 0
	v_mov_b32_e32 v60, 0
	v_mov_b32_e32 v61, 0
	v_mov_b32_e32 v62, 0
	v_mov_b32_e32 v63, 0
	v_mov_b32_e32 v64, 0
	v_mov_b32_e32 v65, 0
	v_mov_b32_e32 v66, 0
	v_mov_b32_e32 v67, 0
	v_mov_b32_e32 v68, 0
	v_mov_b32_e32 v69, 0
	v_mov_b32_e32 v70, 0
	v_mov_b32_e32 v71, 0
	v_mov_b32_e32 v72, 0
	v_mov_b32_e32 v73, 0
	v_mov_b32_e32 v74, 0
	v_mov_b32_e32 v75, 0
	v_mov_b32_e32 v76, 0
	v_mov_b32_e32 v77, 0
	v_mov_b32_e32 v78, 0
	v_mov_b32_e32 v79, 0
	v_mov_b32_e32 v80, 0
	v_mov_b32_e32 v81, 0
	v_mov_b32_e32 v82, 0
	v_mov_b32_e32 v83, 0
	v_mov_b32_e32 v84, 0
	v_mov_b32_e32 v85, 0
	v_mov_b32_e32 v86, 0
	v_mov_b32_e32 v87, 0
	v_mov_b32_e32 v88, 0
	v_mov_b32_e32 v89, 0
	v_mov_b32_e32 v90, 0
	v_mov_b32_e32 v91, 0
	s_mov_b32 s31, 0
	s_mov_b32 s34, 0
	s_mov_b32 s35, s53
	s_mov_b32 s38, s53
	s_mov_b32 s39, 0
	s_mov_b32 s40, 0
	s_mov_b32 s41, s42
	s_and_b32 s4, s38, 31
	s_mul_i32 s4, s4, 0x60000
	s_add_u32 s44, s48, s4
	s_addc_u32 s45, s49, 0
	s_lshr_b32 s4, s38, 5
	s_mul_i32 s4, s4, 0x40000
	s_add_u32 s46, s50, s4
	s_addc_u32 s47, s51, 0
	s_add_u32 m0, s41, 0x0
	s_nop 0
	global_load_lds_dwordx4 v148, s[44:45]
	s_add_u32 m0, s41, 0x2000
	s_nop 0
	global_load_lds_dwordx4 v149, s[44:45]
	s_add_u32 m0, s41, 0x4000
	s_nop 0
	global_load_lds_dwordx4 v150, s[44:45]
	s_add_u32 m0, s41, 0x6000
	s_nop 0
	global_load_lds_dwordx4 v148, s[46:47]
	s_add_u32 m0, s41, 0x8000
	s_nop 0
	global_load_lds_dwordx4 v149, s[46:47]
	s_add_u32 s39, s39, 1
	s_add_u32 s44, s44, 0x80
	s_addc_u32 s45, s45, 0
	s_add_u32 s46, s46, 0x80
	s_addc_u32 s47, s47, 0
	s_cmp_lt_u32 s39, 16
	s_cbranch_scc1 .Lgm_wi_dadv1
	s_mov_b32 s39, 0
	s_add_u32 s4, s38, s52
	s_cmp_lt_u32 s4, s54
	s_cselect_b32 s38, s4, s38
	s_and_b32 s4, s38, 31
	s_mul_i32 s4, s4, 0x60000
	s_add_u32 s44, s48, s4
	s_addc_u32 s45, s49, 0
	s_lshr_b32 s4, s38, 5
	s_mul_i32 s4, s4, 0x40000
	s_add_u32 s46, s50, s4
	s_addc_u32 s47, s51, 0

.Lgm_wi_dadv3:
	ds_read_b128 v[120:123], v152 offset:0
	ds_read_b128 v[124:127], v152 offset:2048
	ds_read_b128 v[128:131], v152 offset:4096
	ds_read_b128 v[132:135], v154 offset:0
	ds_read_b128 v[136:139], v154 offset:2048
	ds_read_b128 v[140:143], v154 offset:4096
	ds_read_b128 v[144:147], v154 offset:6144
	s_waitcnt lgkmcnt(10)
	v_mfma_f32_16x16x32_bf16 v[44:47], v[92:95], v[104:107], v[44:47]
	v_mfma_f32_16x16x32_bf16 v[60:63], v[96:99], v[104:107], v[60:63]
	v_mfma_f32_16x16x32_bf16 v[76:79], v[100:103], v[104:107], v[76:79]
	s_waitcnt lgkmcnt(9)
	v_mfma_f32_16x16x32_bf16 v[48:51], v[92:95], v[108:111], v[48:51]
	v_mfma_f32_16x16x32_bf16 v[64:67], v[96:99], v[108:111], v[64:67]
	v_mfma_f32_16x16x32_bf16 v[80:83], v[100:103], v[108:111], v[80:83]
	s_waitcnt lgkmcnt(8)
	v_mfma_f32_16x16x32_bf16 v[52:55], v[92:95], v[112:115], v[52:55]
	v_mfma_f32_16x16x32_bf16 v[68:71], v[96:99], v[112:115], v[68:71]
	v_mfma_f32_16x16x32_bf16 v[84:87], v[100:103], v[112:115], v[84:87]
	s_waitcnt lgkmcnt(7)
	v_mfma_f32_16x16x32_bf16 v[56:59], v[92:95], v[116:119], v[56:59]
	v_mfma_f32_16x16x32_bf16 v[72:75], v[96:99], v[116:119], v[72:75]
	v_mfma_f32_16x16x32_bf16 v[88:91], v[100:103], v[116:119], v[88:91]
	s_waitcnt lgkmcnt(0)
	s_add_u32 s34, s34, 1
	s_cmp_lt_u32 s34, 16
	s_cbranch_scc1 .Lgm_wi_next
	v_mfma_f32_16x16x32_bf16 v[44:47], v[120:123], v[132:135], v[44:47]
	v_mfma_f32_16x16x32_bf16 v[60:63], v[124:127], v[132:135], v[60:63]
	v_mfma_f32_16x16x32_bf16 v[76:79], v[128:131], v[132:135], v[76:79]
	v_mfma_f32_16x16x32_bf16 v[48:51], v[120:123], v[136:139], v[48:51]
	v_mfma_f32_16x16x32_bf16 v[64:67], v[124:127], v[136:139], v[64:67]
	v_mfma_f32_16x16x32_bf16 v[80:83], v[128:131], v[136:139], v[80:83]
	v_mfma_f32_16x16x32_bf16 v[52:55], v[120:123], v[140:143], v[52:55]
	v_mfma_f32_16x16x32_bf16 v[68:71], v[124:127], v[140:143], v[68:71]
	v_mfma_f32_16x16x32_bf16 v[84:87], v[128:131], v[140:143], v[84:87]
	v_mfma_f32_16x16x32_bf16 v[56:59], v[120:123], v[144:147], v[56:59]
	v_mfma_f32_16x16x32_bf16 v[72:75], v[124:127], v[144:147], v[72:75]
	v_mfma_f32_16x16x32_bf16 v[88:91], v[128:131], v[144:147], v[88:91]
	s_and_b32 s6, s35, 31
	s_mul_i32 s6, s6, 192
	s_lshr_b32 s7, s35, 5
	s_lshl_b32 s7, s7, 7
	s_nop 7
	s_mul_i32 s4, s6, 0x2440
	s_lshl_b32 s5, s7, 2
	s_add_u32 s4, s4, s5
	v_add_u32_e32 v158, s4, v157
	v_add_u32_e32 v161, s7, v159
	s_mov_b32 s4, 0x910
	v_cmp_gt_u32_e32 vcc, s4, v161
	s_mov_b64 s[4:5], exec
	ds_write_b32 v155, v44 offset:0
	ds_write_b32 v155, v45 offset:272
	ds_write_b32 v155, v46 offset:544
	ds_write_b32 v155, v47 offset:816
	ds_write_b32 v155, v48 offset:64
	ds_write_b32 v155, v49 offset:336
	ds_write_b32 v155, v50 offset:608
	ds_write_b32 v155, v51 offset:880
	ds_write_b32 v155, v52 offset:128
	ds_write_b32 v155, v53 offset:400
	ds_write_b32 v155, v54 offset:672
	ds_write_b32 v155, v55 offset:944
	ds_write_b32 v155, v56 offset:192
	ds_write_b32 v155, v57 offset:464
	ds_write_b32 v155, v58 offset:736
	ds_write_b32 v155, v59 offset:1008
	s_waitcnt lgkmcnt(0)
	ds_read_b128 v[16:19], v156 offset:0
	ds_read_b128 v[20:23], v156 offset:1088
	ds_read_b128 v[24:27], v156 offset:2176
	ds_read_b128 v[28:31], v156 offset:3264
	s_waitcnt lgkmcnt(0)
	s_and_b64 exec, s[4:5], vcc
	global_store_dwordx4 v158, v[16:19], s[56:57]
	v_add_u32_e32 v158, 0x9100, v158
	global_store_dwordx4 v158, v[20:23], s[56:57]
	v_add_u32_e32 v158, 0x9100, v158
	global_store_dwordx4 v158, v[24:27], s[56:57]
	v_add_u32_e32 v158, 0x9100, v158
	global_store_dwordx4 v158, v[28:31], s[56:57]
	v_add_u32_e32 v158, 0x9100, v158
	s_mov_b64 exec, s[4:5]
	s_nop 1
	ds_write_b32 v155, v60 offset:0
	ds_write_b32 v155, v61 offset:272
	ds_write_b32 v155, v62 offset:544
	ds_write_b32 v155, v63 offset:816
	ds_write_b32 v155, v64 offset:64
	ds_write_b32 v155, v65 offset:336
	ds_write_b32 v155, v66 offset:608
	ds_write_b32 v155, v67 offset:880
	ds_write_b32 v155, v68 offset:128
	ds_write_b32 v155, v69 offset:400
	ds_write_b32 v155, v70 offset:672
	ds_write_b32 v155, v71 offset:944
	ds_write_b32 v155, v72 offset:192
	ds_write_b32 v155, v73 offset:464
	ds_write_b32 v155, v74 offset:736
	ds_write_b32 v155, v75 offset:1008
	s_waitcnt lgkmcnt(0)
	ds_read_b128 v[16:19], v156 offset:0
	ds_read_b128 v[20:23], v156 offset:1088
	ds_read_b128 v[24:27], v156 offset:2176
	ds_read_b128 v[28:31], v156 offset:3264
	s_waitcnt lgkmcnt(0)
	s_and_b64 exec, s[4:5], vcc
	global_store_dwordx4 v158, v[16:19], s[56:57]
	v_add_u32_e32 v158, 0x9100, v158
	global_store_dwordx4 v158, v[20:23], s[56:57]
	v_add_u32_e32 v158, 0x9100, v158
	global_store_dwordx4 v158, v[24:27], s[56:57]
	v_add_u32_e32 v158, 0x9100, v158
	global_store_dwordx4 v158, v[28:31], s[56:57]
	v_add_u32_e32 v158, 0x9100, v158
	s_mov_b64 exec, s[4:5]
	s_nop 1
	ds_write_b32 v155, v76 offset:0
	ds_write_b32 v155, v77 offset:272
	ds_write_b32 v155, v78 offset:544
	ds_write_b32 v155, v79 offset:816
	ds_write_b32 v155, v80 offset:64
	ds_write_b32 v155, v81 offset:336
	ds_write_b32 v155, v82 offset:608
	ds_write_b32 v155, v83 offset:880
	ds_write_b32 v155, v84 offset:128
	ds_write_b32 v155, v85 offset:400
	ds_write_b32 v155, v86 offset:672
	ds_write_b32 v155, v87 offset:944
	ds_write_b32 v155, v88 offset:192
	ds_write_b32 v155, v89 offset:464
	ds_write_b32 v155, v90 offset:736
	ds_write_b32 v155, v91 offset:1008
	s_waitcnt lgkmcnt(0)
	ds_read_b128 v[16:19], v156 offset:0
	ds_read_b128 v[20:23], v156 offset:1088
	ds_read_b128 v[24:27], v156 offset:2176
	ds_read_b128 v[28:31], v156 offset:3264
	s_waitcnt lgkmcnt(0)
	s_and_b64 exec, s[4:5], vcc
	global_store_dwordx4 v158, v[16:19], s[56:57]
	v_add_u32_e32 v158, 0x9100, v158
	global_store_dwordx4 v158, v[20:23], s[56:57]
	v_add_u32_e32 v158, 0x9100, v158
	global_store_dwordx4 v158, v[24:27], s[56:57]
	v_add_u32_e32 v158, 0x9100, v158
	global_store_dwordx4 v158, v[28:31], s[56:57]
	v_add_u32_e32 v158, 0x9100, v158
	s_mov_b64 exec, s[4:5]
	s_nop 1
	v_mov_b32_e32 v44, 0
	v_mov_b32_e32 v45, 0
	v_mov_b32_e32 v46, 0
	v_mov_b32_e32 v47, 0
	v_mov_b32_e32 v48, 0
	v_mov_b32_e32 v49, 0
	v_mov_b32_e32 v50, 0
	v_mov_b32_e32 v51, 0
	v_mov_b32_e32 v52, 0
	v_mov_b32_e32 v53, 0
	v_mov_b32_e32 v54, 0
	v_mov_b32_e32 v55, 0
	v_mov_b32_e32 v56, 0
	v_mov_b32_e32 v57, 0
	v_mov_b32_e32 v58, 0
	v_mov_b32_e32 v59, 0
	v_mov_b32_e32 v60, 0
	v_mov_b32_e32 v61, 0
	v_mov_b32_e32 v62, 0
	v_mov_b32_e32 v63, 0
	v_mov_b32_e32 v64, 0
	v_mov_b32_e32 v65, 0
	v_mov_b32_e32 v66, 0
	v_mov_b32_e32 v67, 0
	v_mov_b32_e32 v68, 0
	v_mov_b32_e32 v69, 0
	v_mov_b32_e32 v70, 0
	v_mov_b32_e32 v71, 0
	v_mov_b32_e32 v72, 0
	v_mov_b32_e32 v73, 0
	v_mov_b32_e32 v74, 0
	v_mov_b32_e32 v75, 0
	v_mov_b32_e32 v76, 0
	v_mov_b32_e32 v77, 0
	v_mov_b32_e32 v78, 0
	v_mov_b32_e32 v79, 0
	v_mov_b32_e32 v80, 0
	v_mov_b32_e32 v81, 0
	v_mov_b32_e32 v82, 0
	v_mov_b32_e32 v83, 0
	v_mov_b32_e32 v84, 0
	v_mov_b32_e32 v85, 0
	v_mov_b32_e32 v86, 0
	v_mov_b32_e32 v87, 0
	v_mov_b32_e32 v88, 0
	v_mov_b32_e32 v89, 0
	v_mov_b32_e32 v90, 0
	v_mov_b32_e32 v91, 0
	s_mov_b32 s34, 0
	s_add_u32 s35, s35, s52
	s_add_u32 s31, s31, 1
	s_cmp_ge_u32 s31, s30
	s_cbranch_scc1 .Lgm_wi_exit
	s_waitcnt vmcnt(17)
	s_branch .Lgm_wi_rot

.LBB0_192:
	s_andn2_b64 vcc, exec, s[38:39]
	s_cbranch_vccnz .LBB0_560
	v_readlane_b32 s4, v235, 63
	s_cmp_gt_i32 s4, 5
	s_mov_b64 s[38:39], -1
	s_cbranch_scc0 .LBB0_312
	s_branch .LBB0_311

.LBB0_705:
	s_andn2_b64 vcc, exec, s[38:39]
	s_cbranch_vccnz .LBB0_763
	v_readlane_b32 s4, v235, 63
	s_cmp_gt_i32 s4, 0
	s_mov_b64 s[38:39], -1
	s_cbranch_scc0 .LBB0_753
	s_branch .LBB0_752
